# NA: issue tile-A PV tr-reads for pairs 2-4 right after the row-max exchange instead of mid-exp
# baseline (speedup 1.0000x reference)
.LBB0_619:
	s_nop 3
	v_max_f32_e32 v222, v33, v33
	v_max_f32_e32 v223, v32, v32
	v_max_f32_e32 v222, v223, v222
	v_max3_f32 v222, v222, v34, v35
	v_max3_f32 v222, v222, v36, v37
	v_max3_f32 v222, v222, v38, v39
	v_max3_f32 v222, v222, v40, v41
	v_max3_f32 v222, v222, v42, v43
	v_max3_f32 v222, v222, v44, v45
	v_max3_f32 v222, v222, v46, v47
	ds_bpermute_b32 v223, v169, v222
	s_waitcnt lgkmcnt(0)
	s_add_i32 s0, s93, 17
	s_cmp_ge_u32 s0, s84
	s_waitcnt lgkmcnt(0)
	ds_read_b64_tr_b16 v[148:149], v229 offset:64
	ds_read_b64_tr_b16 v[150:151], v229 offset:1216
	ds_read_b64_tr_b16 v[152:153], v229 offset:2304
	ds_read_b64_tr_b16 v[154:155], v229 offset:3456
	ds_read_b64_tr_b16 v[156:157], v229 offset:2368
	ds_read_b64_tr_b16 v[158:159], v229 offset:3520
	v_max3_f32 v233, v140, v222, v223
	v_sub_f32_e32 v32, v32, v233
	v_exp_f32_e32 v234, v32
	v_sub_f32_e32 v32, v33, v233
	v_exp_f32_e32 v235, v32
	v_sub_f32_e32 v32, v34, v233
	v_exp_f32_e32 v236, v32
	v_sub_f32_e32 v32, v35, v233
	v_exp_f32_e32 v237, v32
	v_sub_f32_e32 v32, v36, v233
	v_exp_f32_e32 v238, v32
	v_sub_f32_e32 v32, v37, v233
	v_exp_f32_e32 v239, v32
	v_sub_f32_e32 v32, v38, v233
	v_exp_f32_e32 v240, v32
	v_sub_f32_e32 v32, v39, v233
	v_exp_f32_e32 v241, v32
	v_sub_f32_e32 v32, v40, v233
	v_exp_f32_e32 v242, v32
	v_sub_f32_e32 v32, v41, v233
	v_exp_f32_e32 v243, v32
	v_sub_f32_e32 v32, v42, v233
	v_exp_f32_e32 v244, v32
	v_sub_f32_e32 v32, v43, v233
	ds_read_b64_tr_b16 v[36:37], v229
	ds_read_b64_tr_b16 v[38:39], v229 offset:1152
	v_sub_f32_e32 v140, v140, v233
	v_exp_f32_e32 v245, v32
	v_sub_f32_e32 v32, v44, v233
	v_exp_f32_e32 v140, v140
	v_exp_f32_e32 v246, v32
	v_sub_f32_e32 v32, v45, v233
	v_exp_f32_e32 v247, v32
	v_sub_f32_e32 v32, v46, v233
	v_exp_f32_e32 v248, v32
	v_sub_f32_e32 v32, v47, v233
	v_exp_f32_e32 v249, v32
	v_cvt_pk_bf16_f32 v32, v234, v235
	v_cvt_pk_bf16_f32 v33, v236, v237
	v_cvt_pk_bf16_f32 v34, v238, v239
	v_cvt_pk_bf16_f32 v35, v240, v241
	v_pk_mul_f32 v[30:31], v[30:31], v[140:141] op_sel_hi:[1,0]
	v_pk_mul_f32 v[28:29], v[28:29], v[140:141] op_sel_hi:[1,0]
	v_pk_mul_f32 v[26:27], v[26:27], v[140:141] op_sel_hi:[1,0]
	v_pk_mul_f32 v[24:25], v[24:25], v[140:141] op_sel_hi:[1,0]
	v_pk_mul_f32 v[22:23], v[22:23], v[140:141] op_sel_hi:[1,0]
	v_pk_mul_f32 v[20:21], v[20:21], v[140:141] op_sel_hi:[1,0]
	v_pk_mul_f32 v[18:19], v[18:19], v[140:141] op_sel_hi:[1,0]
	v_pk_mul_f32 v[16:17], v[16:17], v[140:141] op_sel_hi:[1,0]
	v_pk_mul_f32 v[14:15], v[14:15], v[140:141] op_sel_hi:[1,0]
	v_pk_mul_f32 v[12:13], v[12:13], v[140:141] op_sel_hi:[1,0]
	s_waitcnt lgkmcnt(0)
	v_mfma_f32_32x32x16_bf16 v[16:31], v[36:39], v[32:35], v[16:31]
	v_pk_mul_f32 v[10:11], v[10:11], v[140:141] op_sel_hi:[1,0]
	v_pk_mul_f32 v[8:9], v[8:9], v[140:141] op_sel_hi:[1,0]
	v_pk_mul_f32 v[6:7], v[6:7], v[140:141] op_sel_hi:[1,0]
	v_pk_mul_f32 v[4:5], v[4:5], v[140:141] op_sel_hi:[1,0]
	v_pk_mul_f32 v[2:3], v[2:3], v[140:141] op_sel_hi:[1,0]
	v_pk_mul_f32 v[0:1], v[0:1], v[140:141] op_sel_hi:[1,0]
	s_nop 1
	s_waitcnt lgkmcnt(4)
	v_mfma_f32_32x32x16_bf16 v[0:15], v[148:151], v[32:35], v[0:15]
	v_cvt_pk_bf16_f32 v32, v242, v243
	v_cvt_pk_bf16_f32 v33, v244, v245
	v_cvt_pk_bf16_f32 v34, v246, v247
	v_cvt_pk_bf16_f32 v35, v248, v249
	s_nop 1
	s_waitcnt lgkmcnt(2)
	v_mfma_f32_32x32x16_bf16 v[16:31], v[152:155], v[32:35], v[16:31]
	s_waitcnt lgkmcnt(2)
	s_waitcnt lgkmcnt(0)
	s_waitcnt vmcnt(3)
	ds_write_b128 v184, v[96:99] offset:46080
	ds_write_b128 v184, v[100:103] offset:47232
	ds_write_b128 v184, v[104:107] offset:48384
	ds_write_b128 v184, v[108:111] offset:49536
	s_waitcnt lgkmcnt(0)
	ds_read_b128 v[96:99], v185 offset:46080
	ds_read_b128 v[100:103], v185 offset:46112
	ds_read_b128 v[104:107], v185 offset:46144
	ds_read_b128 v[108:111], v185 offset:46176
	ds_write_b128 v184, v[112:115]
	s_waitcnt vmcnt(0)
	ds_write_b128 v184, v[124:127] offset:1152
	ds_write_b128 v184, v[120:123] offset:2304
	ds_write_b128 v184, v[116:119] offset:3456
	v_mfma_f32_32x32x16_bf16 v[0:15], v[156:159], v[32:35], v[0:15]
	s_waitcnt lgkmcnt(4)
	v_mfma_f32_32x32x16_bf16 v[32:47], v[96:99], v[48:51], 0
	v_mfma_f32_32x32x16_bf16 v[32:47], v[100:103], v[52:55], v[32:47]
	v_mfma_f32_32x32x16_bf16 v[32:47], v[104:107], v[56:59], v[32:47]
	v_mfma_f32_32x32x16_bf16 v[32:47], v[108:111], v[60:63], v[32:47]
	s_cbranch_scc1 .LBB0_623
	s_cmp_lt_u32 s81, 13
	s_cselect_b64 vcc, -1, 0
	s_and_b64 vcc, s[76:77], vcc
	s_and_b64 vcc, exec, vcc
	s_mov_b32 s1, s87
	s_cbranch_vccnz .LBB0_622
	s_add_i32 s1, s93, 1
	s_and_b64 vcc, s[76:77], exec
	s_cselect_b32 s0, s1, s0
	s_lshl_b32 s0, s0, 5
	s_add_i32 s1, s0, s86
